# race-free sync rework: seams 1,3,5,7 XCD-local; seams 2,4,6 local release plus cross-XCD arrive awaited before the next phase's first epilogue (covers workspace-aliasing write-after-read); per-class N
# baseline (speedup 1.0000x reference)
; __device__ __forceinline__ unsigned xb_ld(unsigned* p)              { return __hip_atomic_load(p, __ATOMIC_RELAXED, __HIP_MEMORY_SCOPE_AGENT); }
; __device__ __forceinline__ unsigned xb_add(unsigned* p, unsigned v) { return __hip_atomic_fetch_add(p, v, __ATOMIC_RELAXED, __HIP_MEMORY_SCOPE_AGENT); }
; __device__ __forceinline__ void xcd_barrier_complete(unsigned* bar, unsigned x, unsigned& nloc, unsigned& nx) {
;     const unsigned G = gridDim.x;
;     unsigned sum, cnt, mine, sp = 0u;
;     for (;;) {
;         sum = 0u; cnt = 0u; mine = 0u;
; #pragma unroll
;         for (unsigned j = 0; j < 16; ++j) { const unsigned c = xb_ld(&bar[XB_XCNT(j)]); sum += c; cnt += (c > 0u) ? 1u : 0u; mine = (j == x) ? c : mine; }
;         if (sum == G) break;
;         __builtin_amdgcn_s_sleep(1);
;         if ((++sp & 255u) == 0u) { if (xb_ld(&bar[XB_TMO])) break; if (sp > XB_SPIN_CAP) { atomicAdd(&bar[XB_TMO], 1u); break; } }
;     }
;     nloc = mine > 0u ? mine : 1u; nx = cnt > 0u ? cnt : 1u;
; }
; __device__ __forceinline__ void xcd_barrier(const XcdBarrier& b, int tid) {
;     asm volatile("s_waitcnt vmcnt(0)" ::: "memory");
;     __syncthreads();
;     if (tid == 0) {
;         unsigned* bar = b.bar;
;         __builtin_amdgcn_s_waitcnt(0);
;         unsigned nloc = b.st[0], nx = b.st[1];
;         if (nloc == 0u) { xcd_barrier_complete(bar, b.x, nloc, nx); b.st[0] = nloc; b.st[1] = nx; }
;         const unsigned old = xb_add(&bar[XB_XSUB(b.x)], 1u);
;         const unsigned gen = old / nloc;
;         if (old + 1u == (gen + 1u) * nloc) {
;             __builtin_amdgcn_fence(__ATOMIC_RELEASE, "agent");
;             asm volatile("s_waitcnt vmcnt(0)" ::: "memory");
;             const unsigned og = xb_add(&bar[XB_TOP], 1u);
;             const unsigned tg = og / nx;
;             if (og + 1u == (tg + 1u) * nx) xb_add(&bar[XB_TOPGEN], 1u);
;             else XB_SPIN(xb_ld(&bar[XB_TOPGEN]) == tg, bar);
;             __builtin_amdgcn_fence(__ATOMIC_ACQUIRE, "agent");
;             xb_add(&bar[XB_XGEN(b.x)], 1u);
;             asm volatile("s_waitcnt vmcnt(0)" ::: "memory");
;         } else {
;             XB_SPIN(xb_ld(&bar[XB_XGEN(b.x)]) == gen, bar);
.LBB0_331:
	s_or_b64 exec, exec, s[10:11]
	v_mov_b32_e32 v14, 0
	global_load_dword v6, v14, s[40:41] offset:1028 sc1
	global_load_dword v7, v14, s[40:41] offset:1284 sc1
	global_load_dword v8, v14, s[40:41] offset:1540 sc1
	global_load_dword v9, v14, s[40:41] offset:1796 sc1
	global_load_dword v10, v14, s[40:41] offset:2052 sc1
	global_load_dword v11, v14, s[40:41] offset:2308 sc1
	global_load_dword v12, v14, s[40:41] offset:2564 sc1
	global_load_dword v13, v14, s[40:41] offset:2820 sc1
	v_cvt_f32_u32_e32 v4, v2
	s_waitcnt vmcnt(0)
	v_readfirstlane_b32 s0, v3
	s_mov_b32 s12, 1
	s_cmp_eq_u32 s66, 0x100
	s_cselect_b32 s12, s12, 0
	v_readfirstlane_b32 s1, v6
	s_bcnt1_i32_b32 s1, s1
	s_cmp_eq_u32 s1, 1
	s_cselect_b32 s12, s12, 0
	v_readfirstlane_b32 s1, v7
	s_bcnt1_i32_b32 s1, s1
	s_cmp_eq_u32 s1, 1
	s_cselect_b32 s12, s12, 0
	v_readfirstlane_b32 s1, v8
	s_bcnt1_i32_b32 s1, s1
	s_cmp_eq_u32 s1, 1
	s_cselect_b32 s12, s12, 0
	v_readfirstlane_b32 s1, v9
	s_bcnt1_i32_b32 s1, s1
	s_cmp_eq_u32 s1, 1
	s_cselect_b32 s12, s12, 0
	v_readfirstlane_b32 s1, v10
	s_bcnt1_i32_b32 s1, s1
	s_cmp_eq_u32 s1, 1
	s_cselect_b32 s12, s12, 0
	v_readfirstlane_b32 s1, v11
	s_bcnt1_i32_b32 s1, s1
	s_cmp_eq_u32 s1, 1
	s_cselect_b32 s12, s12, 0
	v_readfirstlane_b32 s1, v12
	s_bcnt1_i32_b32 s1, s1
	s_cmp_eq_u32 s1, 1
	s_cselect_b32 s12, s12, 0
	v_readfirstlane_b32 s1, v13
	s_bcnt1_i32_b32 s1, s1
	s_cmp_eq_u32 s1, 1
	s_cselect_b32 s12, s12, 0
	v_writelane_b32 v248, s12, 32
	v_sub_u32_e32 v3, 0, v2
	v_rcp_iflag_f32_e32 v4, v4
	v_add_u32_e32 v5, s0, v1
	v_mul_f32_e32 v4, 0x4f7ffffe, v4
	v_cvt_u32_f32_e32 v4, v4
	v_mul_lo_u32 v1, v3, v4
	v_mul_hi_u32 v1, v4, v1
	v_add_u32_e32 v1, v4, v1
	v_mul_hi_u32 v1, v5, v1
	v_mul_lo_u32 v3, v1, v2
	v_sub_u32_e32 v3, v5, v3
	v_add_u32_e32 v4, 1, v1
	v_cmp_ge_u32_e32 vcc, v3, v2
	s_nop 1
	v_cndmask_b32_e32 v1, v1, v4, vcc
	v_sub_u32_e32 v4, v3, v2
	v_cndmask_b32_e32 v3, v3, v4, vcc
	v_add_u32_e32 v4, 1, v1
	v_cmp_ge_u32_e32 vcc, v3, v2
	v_add_u32_e32 v3, 1, v5
	s_nop 0
	v_cndmask_b32_e32 v1, v1, v4, vcc
	v_mul_lo_u32 v4, v2, v1
	v_add_u32_e32 v2, v4, v2
	v_cmp_ne_u32_e32 vcc, v3, v2
	s_and_saveexec_b64 s[0:1], vcc
	s_xor_b64 s[8:9], exec, s[0:1]
	s_cbranch_execz .LBB0_345
	s_waitcnt lgkmcnt(0)
	v_mov_b32_e32 v0, 0x2000
	global_load_dword v0, v0, s[6:7] offset:1024 sc1
	s_add_u32 s12, s6, 0x2400
	s_addc_u32 s13, s7, 0
	s_waitcnt vmcnt(0)
	v_cmp_eq_u32_e32 vcc, v0, v1
	s_and_saveexec_b64 s[10:11], vcc
	s_cbranch_execz .LBB0_344
	s_mov_b32 s0, 1
	s_mov_b64 s[14:15], 0
	v_mov_b32_e32 v0, 0
	s_branch .LBB0_335

; __device__ __forceinline__ unsigned xb_add(unsigned* p, unsigned v) { return __hip_atomic_fetch_add(p, v, __ATOMIC_RELAXED, __HIP_MEMORY_SCOPE_AGENT); }
; __device__ __forceinline__ void xcd_barrier(const XcdBarrier& b, int tid) {
;     ...
;             __builtin_amdgcn_fence(__ATOMIC_RELEASE, "agent");
;             asm volatile("s_waitcnt vmcnt(0)" ::: "memory");
;             const unsigned og = xb_add(&bar[XB_TOP], 1u);
.Lnowb_2:
	s_waitcnt lgkmcnt(0)
	s_waitcnt vmcnt(0)
	v_mbcnt_lo_u32_b32 v1, s8, 0
	v_mbcnt_hi_u32_b32 v1, s9, v1
	v_cmp_eq_u32_e32 vcc, 0, v1
	s_and_saveexec_b64 s[10:11], vcc
	s_cbranch_execz .LBB0_528
	s_bcnt1_i32_b64 s0, s[8:9]
	v_mov_b32_e32 v2, 0x3000
	v_mov_b32_e32 v3, s0
	global_atomic_add v2, v2, v3, s[40:41] offset:1024 sc0

; #define PG8_STAGE(bufoff, gbase, voff) do { _Pragma("unroll") for (int _i = 0; _i < 2; ++_i) \
;         __builtin_amdgcn_global_load_lds((const unsigned*)((const char*)(gbase) + (voff)[_i]), (PG8_LAS unsigned*)(lds + (bufoff) + ldsw + _i * 8192), 16, 0, 0); } while (0)
; #define PG8_LDA(dst, b, h) do { _Pragma("unroll") for (int m = 0; m < 4; ++m) _Pragma("unroll") for (int k = 0; k < 2; ++k) dst[m][k] = *(const PG8_LAS bf16x8*)(lds + PG8_SA(b, h) + aoff + m * 2048 + k * 1024); } while (0)
; #define PG8_LDB(dst, b, h) do { _Pragma("unroll") for (int n = 0; n < 2; ++n) _Pragma("unroll") for (int k = 0; k < 2; ++k) dst[n][k] = *(const PG8_LAS bf16x8*)(lds + PG8_SB(b, h) + boff + n * 2048 + k * 1024); } while (0)
; #define PG8_MMA(ai, bj, At, Bt) do { __builtin_amdgcn_s_setprio(1); _Pragma("unroll") for (int m = 0; m < 4; ++m) _Pragma("unroll") for (int n = 0; n < 2; ++n) _Pragma("unroll") for (int k = 0; k < 2; ++k) \
;         acc[ai][bj][m][n] = __builtin_amdgcn_mfma_f32_16x16x32_bf16(Bt[n][k], At[m][k], acc[ai][bj][m][n], 0, 0, 0); __builtin_amdgcn_s_setprio(0); } while (0)
; #define PG8_BAR __builtin_amdgcn_s_barrier()
; template <class Epi, class Sched, bool ALIGN_EPI = false, bool SP2 = false>
; __device__ __forceinline__ void gemm_phase(PG8_LAS unsigned char* lds, const Gemm g, const Sched& S, const Epi& E, int tid_in) {
;     ...
;             PG8_LDB(B0, 0, 0); PG8_LDB(B1, 0, 1); PG8_SCHED; PG8_LDA(At, 0, 0); PG8_STAGE(PG8_SA(1, 1), a1 + hstep, voffA);
;             PG8_WAIT_V(8); PG8_WAIT_L(0); PG8_BAR; PG8_MMA(0, 0, At, B0); PG8_MMA(0, 1, At, B1); PG8_BAR; PG8_SCHED;
;             PG8_LDA(At, 0, 1); PG8_STAGE(PG8_SB(0, 0), b2, voffB); PG8_STAGE(PG8_SB(0, 1), b2 + hstep, voffB); PG8_STAGE(PG8_SA(0, 0), a2, voffA);
;             PG8_WAIT_V(8); PG8_WAIT_L(0); PG8_BAR; PG8_MMA(1, 0, At, B0); PG8_MMA(1, 1, At, B1); PG8_BAR; PG8_SCHED;
;             PG8_LDB(B0, 1, 0); PG8_LDB(B1, 1, 1); PG8_SCHED; PG8_LDA(At, 1, 0); PG8_STAGE(PG8_SA(0, 1), a2 + hstep, voffA);
;             PG8_WAIT_V(8); PG8_WAIT_L(0); PG8_BAR; PG8_MMA(0, 0, At, B0); PG8_MMA(0, 1, At, B1); PG8_BAR; PG8_SCHED;
;             PG8_LDA(At, 1, 1); PG8_STAGE(PG8_SB(1, 0), b3, voffB); PG8_STAGE(PG8_SB(1, 1), b3 + hstep, voffB); PG8_STAGE(PG8_SA(1, 0), a3, voffA);
;             PG8_WAIT_V(8); PG8_WAIT_L(0); PG8_BAR; PG8_MMA(1, 0, At, B0); PG8_MMA(1, 1, At, B1); PG8_BAR; PG8_SCHED;
.LBB0_564:
	s_add_u32 s48, s46, 0xfffc0080
	s_addc_u32 s49, s47, -1
	s_cmp_eq_u32 s52, 12
	s_cselect_b32 s51, s0, s49
	s_cselect_b32 s50, s1, s48
	s_cselect_b32 s49, s7, s45
	s_cselect_b32 s48, s31, s35
	s_add_i32 m0, s59, 0xc000
	ds_read_b128 v[128:131], v180
	global_load_lds_dwordx4 v158, s[46:47]
	s_add_i32 m0, s59, 0xe000
	ds_read_b128 v[132:135], v180 offset:1024
	global_load_lds_dwordx4 v160, s[46:47]
	ds_read_b128 v[136:139], v180 offset:2048
	ds_read_b128 v[140:143], v180 offset:3072
	ds_read_b128 v[166:169], v181
	ds_read_b128 v[170:173], v181 offset:1024
	ds_read_b128 v[174:177], v181 offset:2048
	ds_read_b128 v[184:187], v181 offset:3072
	ds_read_b128 v[188:191], v182
	ds_read_b128 v[192:195], v182 offset:1024
	ds_read_b128 v[196:199], v182 offset:2048
	ds_read_b128 v[200:203], v182 offset:3072
	ds_read_b128 v[204:207], v182 offset:4096
	ds_read_b128 v[208:211], v182 offset:5120
	ds_read_b128 v[212:215], v182 offset:6144
	ds_read_b128 v[216:219], v182 offset:7168
	s_waitcnt vmcnt(8)
	s_waitcnt lgkmcnt(0)
	s_barrier
	v_mfma_f32_16x16x32_bf16 v[68:71], v[128:131], v[188:191], v[68:71]
	v_mfma_f32_16x16x32_bf16 v[56:59], v[136:139], v[188:191], v[56:59]
	v_mfma_f32_16x16x32_bf16 v[52:55], v[128:131], v[196:199], v[52:55]
	v_mfma_f32_16x16x32_bf16 v[48:51], v[136:139], v[196:199], v[48:51]
	v_mfma_f32_16x16x32_bf16 v[44:47], v[128:131], v[204:207], v[44:47]
	v_mfma_f32_16x16x32_bf16 v[40:43], v[136:139], v[204:207], v[40:43]
	v_mfma_f32_16x16x32_bf16 v[36:39], v[128:131], v[212:215], v[36:39]
	v_mfma_f32_16x16x32_bf16 v[32:35], v[136:139], v[212:215], v[32:35]
	v_mfma_f32_16x16x32_bf16 v[68:71], v[132:135], v[192:195], v[68:71]
	v_mfma_f32_16x16x32_bf16 v[56:59], v[140:143], v[192:195], v[56:59]
	v_mfma_f32_16x16x32_bf16 v[52:55], v[132:135], v[200:203], v[52:55]
	v_mfma_f32_16x16x32_bf16 v[48:51], v[140:143], v[200:203], v[48:51]
	v_mfma_f32_16x16x32_bf16 v[44:47], v[132:135], v[208:211], v[44:47]
	v_mfma_f32_16x16x32_bf16 v[40:43], v[140:143], v[208:211], v[40:43]
	v_mfma_f32_16x16x32_bf16 v[36:39], v[132:135], v[216:219], v[36:39]
	v_mfma_f32_16x16x32_bf16 v[32:35], v[140:143], v[216:219], v[32:35]
	v_mfma_f32_16x16x32_bf16 v[124:127], v[166:169], v[188:191], v[124:127]
	v_mfma_f32_16x16x32_bf16 v[120:123], v[174:177], v[188:191], v[120:123]
	v_mfma_f32_16x16x32_bf16 v[116:119], v[166:169], v[196:199], v[116:119]
	v_mfma_f32_16x16x32_bf16 v[112:115], v[174:177], v[196:199], v[112:115]
	v_mfma_f32_16x16x32_bf16 v[108:111], v[166:169], v[204:207], v[108:111]
	v_mfma_f32_16x16x32_bf16 v[104:107], v[174:177], v[204:207], v[104:107]
	v_mfma_f32_16x16x32_bf16 v[100:103], v[166:169], v[212:215], v[100:103]
	v_mfma_f32_16x16x32_bf16 v[96:99], v[174:177], v[212:215], v[96:99]
	v_mfma_f32_16x16x32_bf16 v[124:127], v[170:173], v[192:195], v[124:127]
	v_mfma_f32_16x16x32_bf16 v[120:123], v[184:187], v[192:195], v[120:123]
	v_mfma_f32_16x16x32_bf16 v[116:119], v[170:173], v[200:203], v[116:119]
	v_mfma_f32_16x16x32_bf16 v[112:115], v[184:187], v[200:203], v[112:115]
	v_mfma_f32_16x16x32_bf16 v[108:111], v[170:173], v[208:211], v[108:111]
	v_mfma_f32_16x16x32_bf16 v[104:107], v[184:187], v[208:211], v[104:107]
	v_mfma_f32_16x16x32_bf16 v[100:103], v[170:173], v[216:219], v[100:103]
	v_mfma_f32_16x16x32_bf16 v[96:99], v[184:187], v[216:219], v[96:99]
	s_barrier
	s_add_u32 s98, s48, s14
	s_addc_u32 s99, s49, s15
	s_add_u32 s100, s50, s14
	s_addc_u32 s101, s51, s15
	s_add_i32 s53, s77, s29
	s_mov_b32 m0, s53
	ds_read_b128 v[188:191], v182 offset:16384
	global_load_lds_dwordx4 v146, s[48:49]
	s_add_i32 m0, s53, 0x2000
	s_add_u32 s88, s48, 0x40000
	s_addc_u32 s89, s49, 0
	s_add_i32 s53, s78, s29
	global_load_lds_dwordx4 v150, s[48:49]
	s_mov_b32 m0, s53
	ds_read_b128 v[192:195], v182 offset:17408
	global_load_lds_dwordx4 v146, s[88:89]
	s_add_i32 m0, s53, 0x2000
	ds_read_b128 v[196:199], v182 offset:18432
	global_load_lds_dwordx4 v150, s[88:89]
	s_mov_b32 m0, s59
	ds_read_b128 v[200:203], v182 offset:19456
	global_load_lds_dwordx4 v144, s[50:51]
	s_mov_b32 m0, s60
	ds_read_b128 v[204:207], v182 offset:20480
	global_load_lds_dwordx4 v148, s[50:51]
	ds_read_b128 v[208:211], v182 offset:21504
	ds_read_b128 v[212:215], v182 offset:22528
	ds_read_b128 v[216:219], v182 offset:23552
	s_waitcnt vmcnt(8)
	s_waitcnt lgkmcnt(0)
	s_barrier
	v_mfma_f32_16x16x32_bf16 v[28:31], v[128:131], v[188:191], v[28:31]
	v_mfma_f32_16x16x32_bf16 v[24:27], v[136:139], v[188:191], v[24:27]
	v_mfma_f32_16x16x32_bf16 v[20:23], v[128:131], v[196:199], v[20:23]
	v_mfma_f32_16x16x32_bf16 v[16:19], v[136:139], v[196:199], v[16:19]
	v_mfma_f32_16x16x32_bf16 v[12:15], v[128:131], v[204:207], v[12:15]
	v_mfma_f32_16x16x32_bf16 v[8:11], v[136:139], v[204:207], v[8:11]
	v_mfma_f32_16x16x32_bf16 v[4:7], v[128:131], v[212:215], v[4:7]
	v_mfma_f32_16x16x32_bf16 v[0:3], v[136:139], v[212:215], v[0:3]
	v_mfma_f32_16x16x32_bf16 v[28:31], v[132:135], v[192:195], v[28:31]
	v_mfma_f32_16x16x32_bf16 v[24:27], v[140:143], v[192:195], v[24:27]
	v_mfma_f32_16x16x32_bf16 v[20:23], v[132:135], v[200:203], v[20:23]
	v_mfma_f32_16x16x32_bf16 v[16:19], v[140:143], v[200:203], v[16:19]
	v_mfma_f32_16x16x32_bf16 v[12:15], v[132:135], v[208:211], v[12:15]
	v_mfma_f32_16x16x32_bf16 v[8:11], v[140:143], v[208:211], v[8:11]
	v_mfma_f32_16x16x32_bf16 v[4:7], v[132:135], v[216:219], v[4:7]
	v_mfma_f32_16x16x32_bf16 v[0:3], v[140:143], v[216:219], v[0:3]
	v_mfma_f32_16x16x32_bf16 v[92:95], v[166:169], v[188:191], v[92:95]
	v_mfma_f32_16x16x32_bf16 v[88:91], v[174:177], v[188:191], v[88:91]
	v_mfma_f32_16x16x32_bf16 v[84:87], v[166:169], v[196:199], v[84:87]
	v_mfma_f32_16x16x32_bf16 v[80:83], v[174:177], v[196:199], v[80:83]
	v_mfma_f32_16x16x32_bf16 v[76:79], v[166:169], v[204:207], v[76:79]
	v_mfma_f32_16x16x32_bf16 v[72:75], v[174:177], v[204:207], v[72:75]
	v_mfma_f32_16x16x32_bf16 v[64:67], v[166:169], v[212:215], v[64:67]
	v_mfma_f32_16x16x32_bf16 v[60:63], v[174:177], v[212:215], v[60:63]
	v_mfma_f32_16x16x32_bf16 v[92:95], v[170:173], v[192:195], v[92:95]
	v_mfma_f32_16x16x32_bf16 v[88:91], v[184:187], v[192:195], v[88:91]
	v_mfma_f32_16x16x32_bf16 v[84:87], v[170:173], v[200:203], v[84:87]
	v_mfma_f32_16x16x32_bf16 v[80:83], v[184:187], v[200:203], v[80:83]
	v_mfma_f32_16x16x32_bf16 v[76:79], v[170:173], v[208:211], v[76:79]
	v_mfma_f32_16x16x32_bf16 v[72:75], v[184:187], v[208:211], v[72:75]
	v_mfma_f32_16x16x32_bf16 v[64:67], v[170:173], v[216:219], v[64:67]
	v_mfma_f32_16x16x32_bf16 v[60:63], v[184:187], v[216:219], v[60:63]
	s_barrier
; #define PG8_LDA(dst, b, h) do { _Pragma("unroll") for (int m = 0; m < 4; ++m) _Pragma("unroll") for (int k = 0; k < 2; ++k) dst[m][k] = *(const PG8_LAS bf16x8*)(lds + PG8_SA(b, h) + aoff + m * 2048 + k * 1024); } while (0)
; template <class Epi, class Sched, bool ALIGN_EPI = false, bool SP2 = false>
; __device__ __forceinline__ void gemm_phase(PG8_LAS unsigned char* lds, const Gemm g, const Sched& S, const Epi& E, int tid_in) {
;     ...
;             PG8_LDB(B0, 1, 0); PG8_LDB(B1, 1, 1); PG8_SCHED; PG8_LDA(At, 1, 0); PG8_STAGE(PG8_SA(0, 1), a2 + hstep, voffA);
;             PG8_WAIT_V(8); PG8_WAIT_L(0); PG8_BAR; PG8_MMA(0, 0, At, B0); PG8_MMA(0, 1, At, B1); PG8_BAR; PG8_SCHED;
;             PG8_LDA(At, 1, 1); PG8_STAGE(PG8_SB(1, 0), b3, voffB); PG8_STAGE(PG8_SB(1, 1), b3 + hstep, voffB); PG8_STAGE(PG8_SA(1, 0), a3, voffA);
;             PG8_WAIT_V(8); PG8_WAIT_L(0); PG8_BAR; PG8_MMA(1, 0, At, B0); PG8_MMA(1, 1, At, B1); PG8_BAR; PG8_SCHED;
;             } else {
;             PG8_LDB(B0, 0, 0); PG8_SCHED; PG8_LDA(At, 0, 0); PG8_STAGE(PG8_SA(1, 1), a1 + hstep, voffA);
;             PG8_WAIT_L(8); PG8_BAR; PG8_WAIT_L(0); PG8_MMA(0, 0, At, B0); PG8_BAR; PG8_SCHED;
;             PG8_LDB(B1, 0, 1); PG8_STAGE(PG8_SB(0, 0), b2, voffB);
;             PG8_BAR; PG8_WAIT_L(0); PG8_MMA(0, 1, At, B1); PG8_BAR;
;             PG8_LDA(At, 0, 1); PG8_STAGE(PG8_SA(0, 0), a2, voffA);
;             PG8_BAR; PG8_WAIT_L(0); PG8_MMA(1, 0, At, B0); PG8_BAR; PG8_SCHED;
;             PG8_STAGE(PG8_SB(0, 1), b2 + hstep, voffB);
;             PG8_WAIT_V(6); PG8_BAR; PG8_MMA(1, 1, At, B1); PG8_BAR;
;             PG8_LDB(B0, 1, 0); PG8_SCHED; PG8_LDA(At, 1, 0); PG8_STAGE(PG8_SA(0, 1), a2 + hstep, voffA);
;             PG8_WAIT_L(8); PG8_BAR; PG8_WAIT_L(0); PG8_MMA(0, 0, At, B0); PG8_BAR; PG8_SCHED;
;             PG8_LDB(B1, 1, 1); PG8_STAGE(PG8_SB(1, 0), b3, voffB);
;             PG8_BAR; PG8_WAIT_L(0); PG8_MMA(0, 1, At, B1); PG8_BAR;
;             PG8_LDA(At, 1, 1); PG8_STAGE(PG8_SA(1, 0), a3, voffA);
;             PG8_BAR; PG8_WAIT_L(0); PG8_MMA(1, 0, At, B0); PG8_BAR; PG8_SCHED;
;             PG8_STAGE(PG8_SB(1, 1), b3 + hstep, voffB);
;             PG8_WAIT_V(6); PG8_BAR; PG8_MMA(1, 1, At, B1); PG8_BAR;
;             }
;         }
;         if constexpr (ALIGN_EPI) { if (wr == 0) PG8_BAR; }
;         if constexpr (!Epi::AFTER_DRAIN) { E(acc, cur, wr, wc, fr, fq); S.done(cur); }
	s_add_i32 s53, 0, 0x18000
	s_add_i32 s88, 0, 0x1c000
	s_add_u32 s50, s50, 0x40000
	s_addc_u32 s51, s51, 0
	s_mov_b32 m0, s61
	s_nop 0
	global_load_lds_dwordx4 v144, s[50:51]
	s_mov_b32 m0, s62
	s_nop 0
	global_load_lds_dwordx4 v148, s[50:51]
	v_add_u32_e32 v140, s53, v179
	v_add_u32_e32 v184, s88, v179
	ds_read_b128 v[128:131], v140
	ds_read_b128 v[132:135], v140 offset:1024
	ds_read_b128 v[136:139], v140 offset:2048
	ds_read_b128 v[140:143], v140 offset:3072
	ds_read_b128 v[166:169], v184
	ds_read_b128 v[170:173], v184 offset:1024
	ds_read_b128 v[174:177], v184 offset:2048
	ds_read_b128 v[184:187], v184 offset:3072
	ds_read_b128 v[188:191], v182 offset:32768
	ds_read_b128 v[192:195], v182 offset:33792
	ds_read_b128 v[196:199], v182 offset:34816
	ds_read_b128 v[200:203], v182 offset:35840
	ds_read_b128 v[204:207], v182 offset:36864
	ds_read_b128 v[208:211], v182 offset:37888
	ds_read_b128 v[212:215], v182 offset:38912
	ds_read_b128 v[216:219], v182 offset:39936
	s_waitcnt vmcnt(8)
	s_waitcnt lgkmcnt(0)
	s_barrier
	v_mfma_f32_16x16x32_bf16 v[68:71], v[128:131], v[188:191], v[68:71]
	v_mfma_f32_16x16x32_bf16 v[56:59], v[136:139], v[188:191], v[56:59]
	v_mfma_f32_16x16x32_bf16 v[52:55], v[128:131], v[196:199], v[52:55]
	v_mfma_f32_16x16x32_bf16 v[48:51], v[136:139], v[196:199], v[48:51]
	v_mfma_f32_16x16x32_bf16 v[44:47], v[128:131], v[204:207], v[44:47]
	v_mfma_f32_16x16x32_bf16 v[40:43], v[136:139], v[204:207], v[40:43]
	v_mfma_f32_16x16x32_bf16 v[36:39], v[128:131], v[212:215], v[36:39]
	v_mfma_f32_16x16x32_bf16 v[32:35], v[136:139], v[212:215], v[32:35]
	v_mfma_f32_16x16x32_bf16 v[68:71], v[132:135], v[192:195], v[68:71]
	v_mfma_f32_16x16x32_bf16 v[56:59], v[140:143], v[192:195], v[56:59]
	v_mfma_f32_16x16x32_bf16 v[52:55], v[132:135], v[200:203], v[52:55]
	v_mfma_f32_16x16x32_bf16 v[48:51], v[140:143], v[200:203], v[48:51]
	v_mfma_f32_16x16x32_bf16 v[44:47], v[132:135], v[208:211], v[44:47]
	v_mfma_f32_16x16x32_bf16 v[40:43], v[140:143], v[208:211], v[40:43]
	v_mfma_f32_16x16x32_bf16 v[36:39], v[132:135], v[216:219], v[36:39]
	v_mfma_f32_16x16x32_bf16 v[32:35], v[140:143], v[216:219], v[32:35]
	v_mfma_f32_16x16x32_bf16 v[124:127], v[166:169], v[188:191], v[124:127]
	v_mfma_f32_16x16x32_bf16 v[120:123], v[174:177], v[188:191], v[120:123]
	v_mfma_f32_16x16x32_bf16 v[116:119], v[166:169], v[196:199], v[116:119]
	v_mfma_f32_16x16x32_bf16 v[112:115], v[174:177], v[196:199], v[112:115]
	v_mfma_f32_16x16x32_bf16 v[108:111], v[166:169], v[204:207], v[108:111]
	v_mfma_f32_16x16x32_bf16 v[104:107], v[174:177], v[204:207], v[104:107]
	v_mfma_f32_16x16x32_bf16 v[100:103], v[166:169], v[212:215], v[100:103]
	v_mfma_f32_16x16x32_bf16 v[96:99], v[174:177], v[212:215], v[96:99]
	v_mfma_f32_16x16x32_bf16 v[124:127], v[170:173], v[192:195], v[124:127]
	v_mfma_f32_16x16x32_bf16 v[120:123], v[184:187], v[192:195], v[120:123]
	v_mfma_f32_16x16x32_bf16 v[116:119], v[170:173], v[200:203], v[116:119]
	v_mfma_f32_16x16x32_bf16 v[112:115], v[184:187], v[200:203], v[112:115]
	v_mfma_f32_16x16x32_bf16 v[108:111], v[170:173], v[208:211], v[108:111]
	v_mfma_f32_16x16x32_bf16 v[104:107], v[184:187], v[208:211], v[104:107]
	v_mfma_f32_16x16x32_bf16 v[100:103], v[170:173], v[216:219], v[100:103]
	v_mfma_f32_16x16x32_bf16 v[96:99], v[184:187], v[216:219], v[96:99]
	s_barrier
	s_add_i32 s50, s53, s29
	s_mov_b32 m0, s50
	ds_read_b128 v[188:191], v182 offset:49152
	global_load_lds_dwordx4 v146, s[98:99]
	s_add_i32 m0, s50, 0x2000
	s_add_u32 s48, s48, 0x40080
	s_addc_u32 s49, s49, 0
	s_add_i32 s50, s88, s29
	global_load_lds_dwordx4 v150, s[98:99]
	s_mov_b32 m0, s50
	ds_read_b128 v[192:195], v182 offset:50176
	global_load_lds_dwordx4 v146, s[48:49]
	s_add_i32 m0, s50, 0x2000
	ds_read_b128 v[196:199], v182 offset:51200
	global_load_lds_dwordx4 v150, s[48:49]
	s_mov_b32 m0, s63
	ds_read_b128 v[200:203], v182 offset:52224
	global_load_lds_dwordx4 v144, s[100:101]
	s_mov_b32 m0, s64
	ds_read_b128 v[204:207], v182 offset:53248
	global_load_lds_dwordx4 v148, s[100:101]
	ds_read_b128 v[208:211], v182 offset:54272
	ds_read_b128 v[212:215], v182 offset:55296
	ds_read_b128 v[216:219], v182 offset:56320
	s_waitcnt vmcnt(8)
	s_waitcnt lgkmcnt(0)
	s_barrier
	v_mfma_f32_16x16x32_bf16 v[28:31], v[128:131], v[188:191], v[28:31]
	v_mfma_f32_16x16x32_bf16 v[24:27], v[136:139], v[188:191], v[24:27]
	v_mfma_f32_16x16x32_bf16 v[20:23], v[128:131], v[196:199], v[20:23]
	v_mfma_f32_16x16x32_bf16 v[16:19], v[136:139], v[196:199], v[16:19]
	v_mfma_f32_16x16x32_bf16 v[12:15], v[128:131], v[204:207], v[12:15]
	v_mfma_f32_16x16x32_bf16 v[8:11], v[136:139], v[204:207], v[8:11]
	v_mfma_f32_16x16x32_bf16 v[4:7], v[128:131], v[212:215], v[4:7]
	v_mfma_f32_16x16x32_bf16 v[0:3], v[136:139], v[212:215], v[0:3]
	v_mfma_f32_16x16x32_bf16 v[28:31], v[132:135], v[192:195], v[28:31]
	v_mfma_f32_16x16x32_bf16 v[24:27], v[140:143], v[192:195], v[24:27]
	v_mfma_f32_16x16x32_bf16 v[20:23], v[132:135], v[200:203], v[20:23]
	v_mfma_f32_16x16x32_bf16 v[16:19], v[140:143], v[200:203], v[16:19]
	v_mfma_f32_16x16x32_bf16 v[12:15], v[132:135], v[208:211], v[12:15]
	v_mfma_f32_16x16x32_bf16 v[8:11], v[140:143], v[208:211], v[8:11]
	v_mfma_f32_16x16x32_bf16 v[4:7], v[132:135], v[216:219], v[4:7]
	v_mfma_f32_16x16x32_bf16 v[0:3], v[140:143], v[216:219], v[0:3]
	v_mfma_f32_16x16x32_bf16 v[92:95], v[166:169], v[188:191], v[92:95]
	v_mfma_f32_16x16x32_bf16 v[88:91], v[174:177], v[188:191], v[88:91]
	v_mfma_f32_16x16x32_bf16 v[84:87], v[166:169], v[196:199], v[84:87]
	v_mfma_f32_16x16x32_bf16 v[80:83], v[174:177], v[196:199], v[80:83]
	v_mfma_f32_16x16x32_bf16 v[76:79], v[166:169], v[204:207], v[76:79]
	v_mfma_f32_16x16x32_bf16 v[72:75], v[174:177], v[204:207], v[72:75]
	v_mfma_f32_16x16x32_bf16 v[64:67], v[166:169], v[212:215], v[64:67]
	v_mfma_f32_16x16x32_bf16 v[60:63], v[174:177], v[212:215], v[60:63]
	v_mfma_f32_16x16x32_bf16 v[92:95], v[170:173], v[192:195], v[92:95]
	v_mfma_f32_16x16x32_bf16 v[88:91], v[184:187], v[192:195], v[88:91]
	v_mfma_f32_16x16x32_bf16 v[84:87], v[170:173], v[200:203], v[84:87]
	v_mfma_f32_16x16x32_bf16 v[80:83], v[184:187], v[200:203], v[80:83]
	v_mfma_f32_16x16x32_bf16 v[76:79], v[170:173], v[208:211], v[76:79]
	v_mfma_f32_16x16x32_bf16 v[72:75], v[184:187], v[208:211], v[72:75]
	v_mfma_f32_16x16x32_bf16 v[64:67], v[170:173], v[216:219], v[64:67]
	v_mfma_f32_16x16x32_bf16 v[60:63], v[184:187], v[216:219], v[60:63]
	s_barrier
	s_add_i32 s52, s52, 2
	s_add_u32 s46, s46, 0x100
	s_addc_u32 s47, s47, 0
	s_add_u32 s35, s35, 0x100
	s_addc_u32 s45, s45, 0
	s_cmp_gt_u32 s52, 13
	s_cbranch_scc0 .LBB0_564
	s_cmp_eq_u32 s86, 1
	s_cbranch_scc0 .Lww_done_p3
	v_readlane_b32 s98, v248, 0
	s_nop 3
	s_cmp_eq_u32 s98, 0
	s_cbranch_scc0 .Lww_bar_p3
	v_readlane_b32 s98, v248, 32
	s_nop 3
	s_cmp_eq_u32 s98, 1
	s_cbranch_scc0 .Lww_bar_p3
	v_mov_b32_e32 v246, 0x3500
	s_mov_b32 s98, 0
.Lww_loop_p3:
	global_load_dword v247, v246, s[40:41] sc1
	s_waitcnt vmcnt(0)
	v_readfirstlane_b32 s99, v247
	s_nop 3
	s_cmp_ge_u32 s99, 2
	s_cbranch_scc1 .Lww_bar_p3
	s_sleep 1
	s_add_i32 s98, s98, 1
	s_cmp_lt_u32 s98, 0x40000
	s_cbranch_scc1 .Lww_loop_p3

; #define PG8_BAR __builtin_amdgcn_s_barrier()
;     __device__ __forceinline__ void operator()(const f32x4 (&acc)[2][2][4][2], const Unit& u, int wr, int wc, int fr, int fq) const {
;         const int row0 = u.pm * BM + wr * 64 + fr; const int pn = u.pn;
;         if (pn == 19) {
;             if (wc != 0) return;
; template <class Epi, class Sched, bool ALIGN_EPI = false, bool SP2 = false>
; __device__ __forceinline__ void gemm_phase(PG8_LAS unsigned char* lds, const Gemm g, const Sched& S, const Epi& E, int tid_in) {
;     ...
;         if constexpr (ALIGN_EPI) { if (wr == 0) PG8_BAR; }
;         if constexpr (!Epi::AFTER_DRAIN) { E(acc, cur, wr, wc, fr, fq); S.done(cur); }
.Lww_done_p3:
	s_and_b64 vcc, exec, s[16:17]
	s_cbranch_vccnz .LBB0_568
	v_lshl_add_u32 v166, s44, 8, v178
	s_cmp_lg_u32 s6, 19
	s_mov_b64 s[44:45], -1
	s_cbranch_scc1 .LBB0_569

; __device__ __forceinline__ unsigned xb_ld(unsigned* p)              { return __hip_atomic_load(p, __ATOMIC_RELAXED, __HIP_MEMORY_SCOPE_AGENT); }
; __device__ __forceinline__ unsigned xb_add(unsigned* p, unsigned v) { return __hip_atomic_fetch_add(p, v, __ATOMIC_RELAXED, __HIP_MEMORY_SCOPE_AGENT); }
; #define XB_SPIN(cond, bar) do { unsigned _sp = 0; while (cond) { __builtin_amdgcn_s_sleep(1); \
;     if ((++_sp & 255u) == 0u) { if (xb_ld(&(bar)[XB_TMO])) break; if (_sp > XB_SPIN_CAP) { atomicAdd(&(bar)[XB_TMO], 1u); break; } } } } while (0)
; __device__ __forceinline__ void xcd_barrier(const XcdBarrier& b, int tid) {
;     ...
;         const unsigned old = xb_add(&bar[XB_XSUB(b.x)], 1u);
;         const unsigned gen = old / nloc;
;         if (old + 1u == (gen + 1u) * nloc) {
;             __builtin_amdgcn_fence(__ATOMIC_RELEASE, "agent");
;             asm volatile("s_waitcnt vmcnt(0)" ::: "memory");
;             const unsigned og = xb_add(&bar[XB_TOP], 1u);
;             const unsigned tg = og / nx;
;             if (og + 1u == (tg + 1u) * nx) xb_add(&bar[XB_TOPGEN], 1u);
;             else XB_SPIN(xb_ld(&bar[XB_TOPGEN]) == tg, bar);
;             __builtin_amdgcn_fence(__ATOMIC_ACQUIRE, "agent");
;             xb_add(&bar[XB_XGEN(b.x)], 1u);
;             asm volatile("s_waitcnt vmcnt(0)" ::: "memory");
;         } else {
;             XB_SPIN(xb_ld(&bar[XB_XGEN(b.x)]) == gen, bar);
.Lnowb_4:
	s_waitcnt lgkmcnt(0)
	s_waitcnt vmcnt(0)
	v_mbcnt_lo_u32_b32 v1, s6, 0
	v_mbcnt_hi_u32_b32 v1, s7, v1
	v_cmp_eq_u32_e32 vcc, 0, v1
	s_and_saveexec_b64 s[8:9], vcc
	s_cbranch_execz .LBB0_1026
	s_bcnt1_i32_b64 s0, s[6:7]
	v_mov_b32_e32 v2, 0x3000
	v_mov_b32_e32 v3, s0
	global_atomic_add v2, v2, v3, s[40:41] offset:1024 sc0
.LBB0_1026:
	s_or_b64 exec, exec, s[8:9]
	v_cvt_f32_u32_e32 v3, v0
	s_waitcnt vmcnt(0)
	v_readfirstlane_b32 s0, v2
	s_add_u32 s8, s40, 0x3500
	s_addc_u32 s9, s41, 0
	v_rcp_iflag_f32_e32 v3, v3
	v_add_u32_e32 v1, s0, v1
	v_add_u32_e32 v4, 1, v1
	s_mov_b64 s[10:11], -1
	v_mul_f32_e32 v2, 0x4f7ffffe, v3
	v_cvt_u32_f32_e32 v2, v2
	v_sub_u32_e32 v3, 0, v0
	v_mul_lo_u32 v3, v3, v2
	v_mul_hi_u32 v3, v2, v3
	v_add_u32_e32 v2, v2, v3
	v_mul_hi_u32 v2, v1, v2
	v_mul_lo_u32 v3, v2, v0
	v_sub_u32_e32 v1, v1, v3
	v_add_u32_e32 v5, 1, v2
	v_cmp_ge_u32_e32 vcc, v1, v0
	v_sub_u32_e32 v3, v1, v0
	s_nop 0
	v_cndmask_b32_e32 v2, v2, v5, vcc
	v_cndmask_b32_e32 v1, v1, v3, vcc
	v_add_u32_e32 v3, 1, v2
	v_cmp_ge_u32_e32 vcc, v1, v0
	s_nop 1
	v_cndmask_b32_e32 v2, v2, v3, vcc
	v_mul_lo_u32 v1, v0, v2
	v_add_u32_e32 v0, v1, v0
	v_cmp_ne_u32_e32 vcc, v4, v0
	v_mov_b64_e32 v[0:1], s[8:9]
	s_and_saveexec_b64 s[6:7], vcc
	s_cbranch_execz .LBB0_1038
	v_readlane_b32 s0, v248, 32
	s_nop 3
	s_cmp_eq_u32 s0, 1
	s_cbranch_scc0 .Lspin_4
	s_mov_b64 s[10:11], 0
	s_branch .LBB0_1038
.Lspin_4:
	v_mov_b32_e32 v0, 0
	global_load_dword v1, v0, s[8:9] sc1
	s_mov_b64 s[14:15], 0
	s_waitcnt vmcnt(0)
	v_cmp_eq_u32_e32 vcc, v1, v2
	s_and_saveexec_b64 s[12:13], vcc
	s_cbranch_execz .LBB0_1037
	s_add_u32 s10, s40, 0x200
	s_addc_u32 s11, s41, 0
	s_mov_b32 s0, 1
	s_branch .LBB0_1030

; #define PG8_BAR __builtin_amdgcn_s_barrier()
; template <class Epi, class Sched, bool ALIGN_EPI = false, bool SP2 = false>
; __device__ __forceinline__ void gemm_phase(PG8_LAS unsigned char* lds, const Gemm g, const Sched& S, const Epi& E, int tid_in) {
;     ...
;         }
;         if constexpr (ALIGN_EPI) { if (wr == 0) PG8_BAR; }
;         if constexpr (!Epi::AFTER_DRAIN) { E(acc, cur, wr, wc, fr, fq); S.done(cur); }
.LBB0_1063:
	s_cmpk_lg_i32 s46, 0x400
	s_cbranch_scc1 .LBB0_1062
	s_cmp_eq_u32 s62, 1
	s_cbranch_scc0 .Lww_done_p6
	v_readlane_b32 s98, v248, 0
	s_nop 3
	s_cmp_eq_u32 s98, 0
	s_cbranch_scc0 .Lww_bar_p6
	v_readlane_b32 s98, v248, 32
	s_nop 3
	s_cmp_eq_u32 s98, 1
	s_cbranch_scc0 .Lww_bar_p6
	v_mov_b32_e32 v246, 0x3500
	s_mov_b32 s98, 0
.Lww_loop_p6:
	global_load_dword v247, v246, s[40:41] sc1
	s_waitcnt vmcnt(0)
	v_readfirstlane_b32 s99, v247
	s_nop 3
	s_cmp_ge_u32 s99, 3
	s_cbranch_scc1 .Lww_bar_p6
	s_sleep 1
	s_add_i32 s98, s98, 1
	s_cmp_lt_u32 s98, 0x40000
	s_cbranch_scc1 .Lww_loop_p6

; #define PG8_BAR __builtin_amdgcn_s_barrier()
; template <class Epi, class Sched, bool ALIGN_EPI = false, bool SP2 = false>
; __device__ __forceinline__ void gemm_phase(PG8_LAS unsigned char* lds, const Gemm g, const Sched& S, const Epi& E, int tid_in) {
;     ...
;         if constexpr (ALIGN_EPI) { if (wr == 0) PG8_BAR; }
.Lww_done_p6:
	s_andn2_b64 vcc, exec, s[14:15]
	s_cbranch_vccnz .LBB0_1066
	s_barrier

; #define PG8_STAGE(bufoff, gbase, voff) do { _Pragma("unroll") for (int _i = 0; _i < 2; ++_i) \
;         __builtin_amdgcn_global_load_lds((const unsigned*)((const char*)(gbase) + (voff)[_i]), (PG8_LAS unsigned*)(lds + (bufoff) + ldsw + _i * 8192), 16, 0, 0); } while (0)
; #define PG8_LDA(dst, b, h) do { _Pragma("unroll") for (int m = 0; m < 4; ++m) _Pragma("unroll") for (int k = 0; k < 2; ++k) dst[m][k] = *(const PG8_LAS bf16x8*)(lds + PG8_SA(b, h) + aoff + m * 2048 + k * 1024); } while (0)
; #define PG8_LDB(dst, b, h) do { _Pragma("unroll") for (int n = 0; n < 2; ++n) _Pragma("unroll") for (int k = 0; k < 2; ++k) dst[n][k] = *(const PG8_LAS bf16x8*)(lds + PG8_SB(b, h) + boff + n * 2048 + k * 1024); } while (0)
; #define PG8_MMA(ai, bj, At, Bt) do { __builtin_amdgcn_s_setprio(1); _Pragma("unroll") for (int m = 0; m < 4; ++m) _Pragma("unroll") for (int n = 0; n < 2; ++n) _Pragma("unroll") for (int k = 0; k < 2; ++k) \
;         acc[ai][bj][m][n] = __builtin_amdgcn_mfma_f32_16x16x32_bf16(Bt[n][k], At[m][k], acc[ai][bj][m][n], 0, 0, 0); __builtin_amdgcn_s_setprio(0); } while (0)
; #define PG8_BAR __builtin_amdgcn_s_barrier()
; template <class Epi, class Sched, bool ALIGN_EPI = false, bool SP2 = false>
; __device__ __forceinline__ void gemm_phase(PG8_LAS unsigned char* lds, const Gemm g, const Sched& S, const Epi& E, int tid_in) {
;     ...
;             PG8_LDB(B0, 0, 0); PG8_LDB(B1, 0, 1); PG8_SCHED; PG8_LDA(At, 0, 0); PG8_STAGE(PG8_SA(1, 1), a1 + hstep, voffA);
;             PG8_WAIT_V(8); PG8_WAIT_L(0); PG8_BAR; PG8_MMA(0, 0, At, B0); PG8_MMA(0, 1, At, B1); PG8_BAR; PG8_SCHED;
;             PG8_LDA(At, 0, 1); PG8_STAGE(PG8_SB(0, 0), b2, voffB); PG8_STAGE(PG8_SB(0, 1), b2 + hstep, voffB); PG8_STAGE(PG8_SA(0, 0), a2, voffA);
;             PG8_WAIT_V(8); PG8_WAIT_L(0); PG8_BAR; PG8_MMA(1, 0, At, B0); PG8_MMA(1, 1, At, B1); PG8_BAR; PG8_SCHED;
;             PG8_LDB(B0, 1, 0); PG8_LDB(B1, 1, 1); PG8_SCHED; PG8_LDA(At, 1, 0); PG8_STAGE(PG8_SA(0, 1), a2 + hstep, voffA);
;             PG8_WAIT_V(8); PG8_WAIT_L(0); PG8_BAR; PG8_MMA(0, 0, At, B0); PG8_MMA(0, 1, At, B1); PG8_BAR; PG8_SCHED;
;             PG8_LDA(At, 1, 1); PG8_STAGE(PG8_SB(1, 0), b3, voffB); PG8_STAGE(PG8_SB(1, 1), b3 + hstep, voffB); PG8_STAGE(PG8_SA(1, 0), a3, voffA);
;             PG8_WAIT_V(8); PG8_WAIT_L(0); PG8_BAR; PG8_MMA(1, 0, At, B0); PG8_MMA(1, 1, At, B1); PG8_BAR; PG8_SCHED;
.LBB0_1238:
	s_add_u32 s26, s24, 0xfffc0080
	s_addc_u32 s27, s25, -1
	s_cmp_eq_u32 s58, 12
	s_cselect_b32 s29, s17, s27
	s_cselect_b32 s28, s54, s26
	s_cselect_b32 s27, s15, s57
	s_cselect_b32 s26, s55, s56
	s_add_i32 m0, s23, 0xc000
	ds_read_b128 v[144:147], v154
	global_load_lds_dwordx4 v136, s[24:25]
	s_add_i32 m0, s23, 0xe000
	ds_read_b128 v[158:161], v154 offset:1024
	global_load_lds_dwordx4 v138, s[24:25]
	ds_read_b128 v[162:165], v154 offset:2048
	ds_read_b128 v[166:169], v154 offset:3072
	ds_read_b128 v[170:173], v155
	ds_read_b128 v[174:177], v155 offset:1024
	ds_read_b128 v[178:181], v155 offset:2048
	ds_read_b128 v[182:185], v155 offset:3072
	ds_read_b128 v[186:189], v156
	ds_read_b128 v[190:193], v156 offset:1024
	ds_read_b128 v[194:197], v156 offset:2048
	ds_read_b128 v[198:201], v156 offset:3072
	ds_read_b128 v[202:205], v156 offset:4096
	ds_read_b128 v[206:209], v156 offset:5120
	ds_read_b128 v[210:213], v156 offset:6144
	ds_read_b128 v[214:217], v156 offset:7168
	s_waitcnt vmcnt(8)
	s_waitcnt lgkmcnt(0)
	s_barrier
	v_mfma_f32_16x16x32_bf16 v[124:127], v[144:147], v[186:189], v[124:127]
	v_mfma_f32_16x16x32_bf16 v[120:123], v[162:165], v[186:189], v[120:123]
	v_mfma_f32_16x16x32_bf16 v[108:111], v[144:147], v[194:197], v[108:111]
	v_mfma_f32_16x16x32_bf16 v[104:107], v[162:165], v[194:197], v[104:107]
	v_mfma_f32_16x16x32_bf16 v[92:95], v[144:147], v[202:205], v[92:95]
	v_mfma_f32_16x16x32_bf16 v[88:91], v[162:165], v[202:205], v[88:91]
	v_mfma_f32_16x16x32_bf16 v[76:79], v[144:147], v[210:213], v[76:79]
	v_mfma_f32_16x16x32_bf16 v[72:75], v[162:165], v[210:213], v[72:75]
	v_mfma_f32_16x16x32_bf16 v[124:127], v[158:161], v[190:193], v[124:127]
	v_mfma_f32_16x16x32_bf16 v[120:123], v[166:169], v[190:193], v[120:123]
	v_mfma_f32_16x16x32_bf16 v[108:111], v[158:161], v[198:201], v[108:111]
	v_mfma_f32_16x16x32_bf16 v[104:107], v[166:169], v[198:201], v[104:107]
	v_mfma_f32_16x16x32_bf16 v[92:95], v[158:161], v[206:209], v[92:95]
	v_mfma_f32_16x16x32_bf16 v[88:91], v[166:169], v[206:209], v[88:91]
	v_mfma_f32_16x16x32_bf16 v[76:79], v[158:161], v[214:217], v[76:79]
	v_mfma_f32_16x16x32_bf16 v[72:75], v[166:169], v[214:217], v[72:75]
	v_mfma_f32_16x16x32_bf16 v[116:119], v[170:173], v[186:189], v[116:119]
	v_mfma_f32_16x16x32_bf16 v[112:115], v[178:181], v[186:189], v[112:115]
	v_mfma_f32_16x16x32_bf16 v[100:103], v[170:173], v[194:197], v[100:103]
	v_mfma_f32_16x16x32_bf16 v[96:99], v[178:181], v[194:197], v[96:99]
	v_mfma_f32_16x16x32_bf16 v[84:87], v[170:173], v[202:205], v[84:87]
	v_mfma_f32_16x16x32_bf16 v[80:83], v[178:181], v[202:205], v[80:83]
	v_mfma_f32_16x16x32_bf16 v[68:71], v[170:173], v[210:213], v[68:71]
	v_mfma_f32_16x16x32_bf16 v[64:67], v[178:181], v[210:213], v[64:67]
	v_mfma_f32_16x16x32_bf16 v[116:119], v[174:177], v[190:193], v[116:119]
	v_mfma_f32_16x16x32_bf16 v[112:115], v[182:185], v[190:193], v[112:115]
	v_mfma_f32_16x16x32_bf16 v[100:103], v[174:177], v[198:201], v[100:103]
	v_mfma_f32_16x16x32_bf16 v[96:99], v[182:185], v[198:201], v[96:99]
	v_mfma_f32_16x16x32_bf16 v[84:87], v[174:177], v[206:209], v[84:87]
	v_mfma_f32_16x16x32_bf16 v[80:83], v[182:185], v[206:209], v[80:83]
	v_mfma_f32_16x16x32_bf16 v[68:71], v[174:177], v[214:217], v[68:71]
	v_mfma_f32_16x16x32_bf16 v[64:67], v[182:185], v[214:217], v[64:67]
	s_barrier
	s_add_u32 s98, s26, s10
	s_addc_u32 s99, s27, s11
	s_add_u32 s100, s28, s10
	s_addc_u32 s101, s29, s11
	s_add_i32 s59, s47, s0
	s_mov_b32 m0, s59
	ds_read_b128 v[186:189], v156 offset:16384
	global_load_lds_dwordx4 v132, s[26:27]
	s_add_i32 m0, s59, 0x2000
	s_add_u32 s60, s26, 0x40000
	s_addc_u32 s61, s27, 0
	s_add_i32 s59, s48, s0
	global_load_lds_dwordx4 v128, s[26:27]
	s_mov_b32 m0, s59
	ds_read_b128 v[190:193], v156 offset:17408
	global_load_lds_dwordx4 v132, s[60:61]
	s_add_i32 m0, s59, 0x2000
	ds_read_b128 v[194:197], v156 offset:18432
	global_load_lds_dwordx4 v128, s[60:61]
	s_mov_b32 m0, s23
	ds_read_b128 v[198:201], v156 offset:19456
	global_load_lds_dwordx4 v134, s[28:29]
	s_mov_b32 m0, s37
	ds_read_b128 v[202:205], v156 offset:20480
	global_load_lds_dwordx4 v130, s[28:29]
	ds_read_b128 v[206:209], v156 offset:21504
	ds_read_b128 v[210:213], v156 offset:22528
	ds_read_b128 v[214:217], v156 offset:23552
	s_waitcnt vmcnt(8)
	s_waitcnt lgkmcnt(0)
	s_barrier
	v_mfma_f32_16x16x32_bf16 v[60:63], v[144:147], v[186:189], v[60:63]
	v_mfma_f32_16x16x32_bf16 v[56:59], v[162:165], v[186:189], v[56:59]
	v_mfma_f32_16x16x32_bf16 v[44:47], v[144:147], v[194:197], v[44:47]
	v_mfma_f32_16x16x32_bf16 v[40:43], v[162:165], v[194:197], v[40:43]
	v_mfma_f32_16x16x32_bf16 v[28:31], v[144:147], v[202:205], v[28:31]
	v_mfma_f32_16x16x32_bf16 v[24:27], v[162:165], v[202:205], v[24:27]
	v_mfma_f32_16x16x32_bf16 v[12:15], v[144:147], v[210:213], v[12:15]
	v_mfma_f32_16x16x32_bf16 v[8:11], v[162:165], v[210:213], v[8:11]
	v_mfma_f32_16x16x32_bf16 v[60:63], v[158:161], v[190:193], v[60:63]
	v_mfma_f32_16x16x32_bf16 v[56:59], v[166:169], v[190:193], v[56:59]
	v_mfma_f32_16x16x32_bf16 v[44:47], v[158:161], v[198:201], v[44:47]
	v_mfma_f32_16x16x32_bf16 v[40:43], v[166:169], v[198:201], v[40:43]
	v_mfma_f32_16x16x32_bf16 v[28:31], v[158:161], v[206:209], v[28:31]
	v_mfma_f32_16x16x32_bf16 v[24:27], v[166:169], v[206:209], v[24:27]
	v_mfma_f32_16x16x32_bf16 v[12:15], v[158:161], v[214:217], v[12:15]
	v_mfma_f32_16x16x32_bf16 v[8:11], v[166:169], v[214:217], v[8:11]
	v_mfma_f32_16x16x32_bf16 v[52:55], v[170:173], v[186:189], v[52:55]
	v_mfma_f32_16x16x32_bf16 v[48:51], v[178:181], v[186:189], v[48:51]
	v_mfma_f32_16x16x32_bf16 v[36:39], v[170:173], v[194:197], v[36:39]
	v_mfma_f32_16x16x32_bf16 v[32:35], v[178:181], v[194:197], v[32:35]
	v_mfma_f32_16x16x32_bf16 v[20:23], v[170:173], v[202:205], v[20:23]
	v_mfma_f32_16x16x32_bf16 v[16:19], v[178:181], v[202:205], v[16:19]
	v_mfma_f32_16x16x32_bf16 v[4:7], v[170:173], v[210:213], v[4:7]
	v_mfma_f32_16x16x32_bf16 v[0:3], v[178:181], v[210:213], v[0:3]
	v_mfma_f32_16x16x32_bf16 v[52:55], v[174:177], v[190:193], v[52:55]
	v_mfma_f32_16x16x32_bf16 v[48:51], v[182:185], v[190:193], v[48:51]
	v_mfma_f32_16x16x32_bf16 v[36:39], v[174:177], v[198:201], v[36:39]
	v_mfma_f32_16x16x32_bf16 v[32:35], v[182:185], v[198:201], v[32:35]
	v_mfma_f32_16x16x32_bf16 v[20:23], v[174:177], v[206:209], v[20:23]
	v_mfma_f32_16x16x32_bf16 v[16:19], v[182:185], v[206:209], v[16:19]
	v_mfma_f32_16x16x32_bf16 v[4:7], v[174:177], v[214:217], v[4:7]
	v_mfma_f32_16x16x32_bf16 v[0:3], v[182:185], v[214:217], v[0:3]
	s_barrier
; #define PG8_LDA(dst, b, h) do { _Pragma("unroll") for (int m = 0; m < 4; ++m) _Pragma("unroll") for (int k = 0; k < 2; ++k) dst[m][k] = *(const PG8_LAS bf16x8*)(lds + PG8_SA(b, h) + aoff + m * 2048 + k * 1024); } while (0)
; template <class Epi, class Sched, bool ALIGN_EPI = false, bool SP2 = false>
; __device__ __forceinline__ void gemm_phase(PG8_LAS unsigned char* lds, const Gemm g, const Sched& S, const Epi& E, int tid_in) {
;     ...
;             PG8_LDB(B0, 1, 0); PG8_LDB(B1, 1, 1); PG8_SCHED; PG8_LDA(At, 1, 0); PG8_STAGE(PG8_SA(0, 1), a2 + hstep, voffA);
;             PG8_WAIT_V(8); PG8_WAIT_L(0); PG8_BAR; PG8_MMA(0, 0, At, B0); PG8_MMA(0, 1, At, B1); PG8_BAR; PG8_SCHED;
;             PG8_LDA(At, 1, 1); PG8_STAGE(PG8_SB(1, 0), b3, voffB); PG8_STAGE(PG8_SB(1, 1), b3 + hstep, voffB); PG8_STAGE(PG8_SA(1, 0), a3, voffA);
;             PG8_WAIT_V(8); PG8_WAIT_L(0); PG8_BAR; PG8_MMA(1, 0, At, B0); PG8_MMA(1, 1, At, B1); PG8_BAR; PG8_SCHED;
;             } else {
;             PG8_LDB(B0, 0, 0); PG8_SCHED; PG8_LDA(At, 0, 0); PG8_STAGE(PG8_SA(1, 1), a1 + hstep, voffA);
;             PG8_WAIT_L(8); PG8_BAR; PG8_WAIT_L(0); PG8_MMA(0, 0, At, B0); PG8_BAR; PG8_SCHED;
;             PG8_LDB(B1, 0, 1); PG8_STAGE(PG8_SB(0, 0), b2, voffB);
;             PG8_BAR; PG8_WAIT_L(0); PG8_MMA(0, 1, At, B1); PG8_BAR;
;             PG8_LDA(At, 0, 1); PG8_STAGE(PG8_SA(0, 0), a2, voffA);
;             PG8_BAR; PG8_WAIT_L(0); PG8_MMA(1, 0, At, B0); PG8_BAR; PG8_SCHED;
;             PG8_STAGE(PG8_SB(0, 1), b2 + hstep, voffB);
;             PG8_WAIT_V(6); PG8_BAR; PG8_MMA(1, 1, At, B1); PG8_BAR;
;             PG8_LDB(B0, 1, 0); PG8_SCHED; PG8_LDA(At, 1, 0); PG8_STAGE(PG8_SA(0, 1), a2 + hstep, voffA);
;             PG8_WAIT_L(8); PG8_BAR; PG8_WAIT_L(0); PG8_MMA(0, 0, At, B0); PG8_BAR; PG8_SCHED;
;             PG8_LDB(B1, 1, 1); PG8_STAGE(PG8_SB(1, 0), b3, voffB);
;             PG8_BAR; PG8_WAIT_L(0); PG8_MMA(0, 1, At, B1); PG8_BAR;
;             PG8_LDA(At, 1, 1); PG8_STAGE(PG8_SA(1, 0), a3, voffA);
;             PG8_BAR; PG8_WAIT_L(0); PG8_MMA(1, 0, At, B0); PG8_BAR; PG8_SCHED;
;             PG8_STAGE(PG8_SB(1, 1), b3 + hstep, voffB);
;             PG8_WAIT_V(6); PG8_BAR; PG8_MMA(1, 1, At, B1); PG8_BAR;
;             }
;         }
;         if constexpr (ALIGN_EPI) { if (wr == 0) PG8_BAR; }
;         if constexpr (!Epi::AFTER_DRAIN) { E(acc, cur, wr, wc, fr, fq); S.done(cur); }
	s_add_i32 s59, 0, 0x18000
	s_add_i32 s60, 0, 0x1c000
	s_add_u32 s28, s28, 0x40000
	s_addc_u32 s29, s29, 0
	s_mov_b32 m0, s38
	v_add_u32_e32 v157, s59, v151
	global_load_lds_dwordx4 v134, s[28:29]
	s_mov_b32 m0, s39
	ds_read_b128 v[144:147], v157
	global_load_lds_dwordx4 v130, s[28:29]
	ds_read_b128 v[158:161], v157 offset:1024
	ds_read_b128 v[162:165], v157 offset:2048
	ds_read_b128 v[166:169], v157 offset:3072
	v_add_u32_e32 v157, s60, v151
	ds_read_b128 v[170:173], v157
	ds_read_b128 v[174:177], v157 offset:1024
	ds_read_b128 v[178:181], v157 offset:2048
	ds_read_b128 v[182:185], v157 offset:3072
	ds_read_b128 v[186:189], v156 offset:32768
	ds_read_b128 v[190:193], v156 offset:33792
	ds_read_b128 v[194:197], v156 offset:34816
	ds_read_b128 v[198:201], v156 offset:35840
	ds_read_b128 v[202:205], v156 offset:36864
	ds_read_b128 v[206:209], v156 offset:37888
	ds_read_b128 v[210:213], v156 offset:38912
	ds_read_b128 v[214:217], v156 offset:39936
	s_waitcnt vmcnt(8)
	s_waitcnt lgkmcnt(0)
	s_barrier
	v_mfma_f32_16x16x32_bf16 v[124:127], v[144:147], v[186:189], v[124:127]
	v_mfma_f32_16x16x32_bf16 v[120:123], v[162:165], v[186:189], v[120:123]
	v_mfma_f32_16x16x32_bf16 v[108:111], v[144:147], v[194:197], v[108:111]
	v_mfma_f32_16x16x32_bf16 v[104:107], v[162:165], v[194:197], v[104:107]
	v_mfma_f32_16x16x32_bf16 v[92:95], v[144:147], v[202:205], v[92:95]
	v_mfma_f32_16x16x32_bf16 v[88:91], v[162:165], v[202:205], v[88:91]
	v_mfma_f32_16x16x32_bf16 v[76:79], v[144:147], v[210:213], v[76:79]
	v_mfma_f32_16x16x32_bf16 v[72:75], v[162:165], v[210:213], v[72:75]
	v_mfma_f32_16x16x32_bf16 v[124:127], v[158:161], v[190:193], v[124:127]
	v_mfma_f32_16x16x32_bf16 v[120:123], v[166:169], v[190:193], v[120:123]
	v_mfma_f32_16x16x32_bf16 v[108:111], v[158:161], v[198:201], v[108:111]
	v_mfma_f32_16x16x32_bf16 v[104:107], v[166:169], v[198:201], v[104:107]
	v_mfma_f32_16x16x32_bf16 v[92:95], v[158:161], v[206:209], v[92:95]
	v_mfma_f32_16x16x32_bf16 v[88:91], v[166:169], v[206:209], v[88:91]
	v_mfma_f32_16x16x32_bf16 v[76:79], v[158:161], v[214:217], v[76:79]
	v_mfma_f32_16x16x32_bf16 v[72:75], v[166:169], v[214:217], v[72:75]
	v_mfma_f32_16x16x32_bf16 v[116:119], v[170:173], v[186:189], v[116:119]
	v_mfma_f32_16x16x32_bf16 v[112:115], v[178:181], v[186:189], v[112:115]
	v_mfma_f32_16x16x32_bf16 v[100:103], v[170:173], v[194:197], v[100:103]
	v_mfma_f32_16x16x32_bf16 v[96:99], v[178:181], v[194:197], v[96:99]
	v_mfma_f32_16x16x32_bf16 v[84:87], v[170:173], v[202:205], v[84:87]
	v_mfma_f32_16x16x32_bf16 v[80:83], v[178:181], v[202:205], v[80:83]
	v_mfma_f32_16x16x32_bf16 v[68:71], v[170:173], v[210:213], v[68:71]
	v_mfma_f32_16x16x32_bf16 v[64:67], v[178:181], v[210:213], v[64:67]
	v_mfma_f32_16x16x32_bf16 v[116:119], v[174:177], v[190:193], v[116:119]
	v_mfma_f32_16x16x32_bf16 v[112:115], v[182:185], v[190:193], v[112:115]
	v_mfma_f32_16x16x32_bf16 v[100:103], v[174:177], v[198:201], v[100:103]
	v_mfma_f32_16x16x32_bf16 v[96:99], v[182:185], v[198:201], v[96:99]
	v_mfma_f32_16x16x32_bf16 v[84:87], v[174:177], v[206:209], v[84:87]
	v_mfma_f32_16x16x32_bf16 v[80:83], v[182:185], v[206:209], v[80:83]
	v_mfma_f32_16x16x32_bf16 v[68:71], v[174:177], v[214:217], v[68:71]
	v_mfma_f32_16x16x32_bf16 v[64:67], v[182:185], v[214:217], v[64:67]
	s_barrier
	s_add_i32 s28, s59, s0
	s_mov_b32 m0, s28
	ds_read_b128 v[186:189], v156 offset:49152
	global_load_lds_dwordx4 v132, s[98:99]
	s_add_i32 m0, s28, 0x2000
	s_add_u32 s26, s26, 0x40080
	s_addc_u32 s27, s27, 0
	s_add_i32 s28, s60, s0
	global_load_lds_dwordx4 v128, s[98:99]
	s_mov_b32 m0, s28
	ds_read_b128 v[190:193], v156 offset:50176
	global_load_lds_dwordx4 v132, s[26:27]
	s_add_i32 m0, s28, 0x2000
	ds_read_b128 v[194:197], v156 offset:51200
	global_load_lds_dwordx4 v128, s[26:27]
	s_mov_b32 m0, s44
	ds_read_b128 v[198:201], v156 offset:52224
	global_load_lds_dwordx4 v134, s[100:101]
	s_mov_b32 m0, s45
	ds_read_b128 v[202:205], v156 offset:53248
	global_load_lds_dwordx4 v130, s[100:101]
	ds_read_b128 v[206:209], v156 offset:54272
	ds_read_b128 v[210:213], v156 offset:55296
	ds_read_b128 v[214:217], v156 offset:56320
	s_waitcnt vmcnt(8)
	s_waitcnt lgkmcnt(0)
	s_barrier
	v_mfma_f32_16x16x32_bf16 v[60:63], v[144:147], v[186:189], v[60:63]
	v_mfma_f32_16x16x32_bf16 v[56:59], v[162:165], v[186:189], v[56:59]
	v_mfma_f32_16x16x32_bf16 v[44:47], v[144:147], v[194:197], v[44:47]
	v_mfma_f32_16x16x32_bf16 v[40:43], v[162:165], v[194:197], v[40:43]
	v_mfma_f32_16x16x32_bf16 v[28:31], v[144:147], v[202:205], v[28:31]
	v_mfma_f32_16x16x32_bf16 v[24:27], v[162:165], v[202:205], v[24:27]
	v_mfma_f32_16x16x32_bf16 v[12:15], v[144:147], v[210:213], v[12:15]
	v_mfma_f32_16x16x32_bf16 v[8:11], v[162:165], v[210:213], v[8:11]
	v_mfma_f32_16x16x32_bf16 v[60:63], v[158:161], v[190:193], v[60:63]
	v_mfma_f32_16x16x32_bf16 v[56:59], v[166:169], v[190:193], v[56:59]
	v_mfma_f32_16x16x32_bf16 v[44:47], v[158:161], v[198:201], v[44:47]
	v_mfma_f32_16x16x32_bf16 v[40:43], v[166:169], v[198:201], v[40:43]
	v_mfma_f32_16x16x32_bf16 v[28:31], v[158:161], v[206:209], v[28:31]
	v_mfma_f32_16x16x32_bf16 v[24:27], v[166:169], v[206:209], v[24:27]
	v_mfma_f32_16x16x32_bf16 v[12:15], v[158:161], v[214:217], v[12:15]
	v_mfma_f32_16x16x32_bf16 v[8:11], v[166:169], v[214:217], v[8:11]
	v_mfma_f32_16x16x32_bf16 v[52:55], v[170:173], v[186:189], v[52:55]
	v_mfma_f32_16x16x32_bf16 v[48:51], v[178:181], v[186:189], v[48:51]
	v_mfma_f32_16x16x32_bf16 v[36:39], v[170:173], v[194:197], v[36:39]
	v_mfma_f32_16x16x32_bf16 v[32:35], v[178:181], v[194:197], v[32:35]
	v_mfma_f32_16x16x32_bf16 v[20:23], v[170:173], v[202:205], v[20:23]
	v_mfma_f32_16x16x32_bf16 v[16:19], v[178:181], v[202:205], v[16:19]
	v_mfma_f32_16x16x32_bf16 v[4:7], v[170:173], v[210:213], v[4:7]
	v_mfma_f32_16x16x32_bf16 v[0:3], v[178:181], v[210:213], v[0:3]
	v_mfma_f32_16x16x32_bf16 v[52:55], v[174:177], v[190:193], v[52:55]
	v_mfma_f32_16x16x32_bf16 v[48:51], v[182:185], v[190:193], v[48:51]
	v_mfma_f32_16x16x32_bf16 v[36:39], v[174:177], v[198:201], v[36:39]
	v_mfma_f32_16x16x32_bf16 v[32:35], v[182:185], v[198:201], v[32:35]
	v_mfma_f32_16x16x32_bf16 v[20:23], v[174:177], v[206:209], v[20:23]
	v_mfma_f32_16x16x32_bf16 v[16:19], v[182:185], v[206:209], v[16:19]
	v_mfma_f32_16x16x32_bf16 v[4:7], v[174:177], v[214:217], v[4:7]
	v_mfma_f32_16x16x32_bf16 v[0:3], v[182:185], v[214:217], v[0:3]
	s_barrier
	s_add_i32 s58, s58, 2
	s_add_u32 s24, s24, 0x100
	s_addc_u32 s25, s25, 0
	s_add_u32 s56, s56, 0x100
	s_addc_u32 s57, s57, 0
	s_cmp_gt_u32 s58, 13
	s_cbranch_scc0 .LBB0_1238
	s_cmp_eq_u32 s50, 1
	s_cbranch_scc0 .Lww_done_p9
	v_readlane_b32 s98, v248, 0
	s_nop 3
	s_cmp_eq_u32 s98, 0
	s_cbranch_scc0 .Lww_bar_p9
	v_readlane_b32 s98, v248, 32
	s_nop 3
	s_cmp_eq_u32 s98, 1
	s_cbranch_scc0 .Lww_bar_p9
	v_mov_b32_e32 v246, 0x3500
	s_mov_b32 s98, 0
.Lww_loop_p9:
	global_load_dword v247, v246, s[40:41] sc1
	s_waitcnt vmcnt(0)
	v_readfirstlane_b32 s99, v247
	s_nop 3
	s_cmp_ge_u32 s99, 4
	s_cbranch_scc1 .Lww_bar_p9
	s_sleep 1
	s_add_i32 s98, s98, 1
	s_cmp_lt_u32 s98, 0x40000
	s_cbranch_scc1 .Lww_loop_p9

; #define PG8_BAR __builtin_amdgcn_s_barrier()
; template <class Epi, class Sched, bool ALIGN_EPI = false, bool SP2 = false>
; __device__ __forceinline__ void gemm_phase(PG8_LAS unsigned char* lds, const Gemm g, const Sched& S, const Epi& E, int tid_in) {
;     ...
;         if constexpr (ALIGN_EPI) { if (wr == 0) PG8_BAR; }
.Lww_done_p9:
	s_and_b64 vcc, exec, s[12:13]
	s_cbranch_vccz .LBB0_1241
	s_barrier
